# code placement: two 4-byte pads so the in-proj K-loop head keeps the baseline's byte phase mod 8 (was shifted by 4), later loops unchanged
# speedup vs baseline: 1.0026x; 1.0026x over previous
; #define LAS __attribute__((address_space(3)))
;     __host__ __device__ bool next(int i, Unit& u) const {
;         const long L = (long)i * G + c; if (L >= nwg) return false;
;         int wgid = (int)L; { const int q = nwg / NXCD, r = nwg % NXCD, xcd = wgid % NXCD, off = wgid / NXCD; wgid = (xcd < r ? xcd * (q + 1) : r * (q + 1) + (xcd - r) * q) + off; }
;         const int nig = wgm * nN, gid = wgid / nig, fm = gid * wgm, gsz = (nM - fm) < wgm ? (nM - fm) : wgm;
;         u.pm = fm + ((wgid % nig) % gsz); u.pn = (wgid % nig) / gsz; if (halves) { const int x = u.pm >> 3, j = u.pm & 7; u.pm = (j >> 2) * 32 + 4 * x + (j & 3); } u.kh = 0; u.slot = i; return true;
; __global__ void __launch_bounds__(NT, 2) fwd_mega(Args A) {
;     ...
;     const int cid = __builtin_amdgcn_readfirstlane((int)((LAS unsigned*)(lds + LDS_BARST))[3]);
;     const int vcu2 = (G % 8 == 0) ? (cid % 8) * (G / 8) + cid / 8 : cid;
;     const bool hwx = __builtin_amdgcn_readfirstlane((int)((LAS unsigned*)(lds + LDS_BARST))[4]) != 0;
;     {
;         pg8::Gemm g{XB, WinT, T, INW, D, D}; pg8::StaticOrder S; S.init(T, INW, G, cid, 4);
.Lcvb_skip:
	s_nop 0
	s_add_i32 s0, 0, 0x23fd0
	v_mov_b32_e32 v0, s0
	ds_read_b32 v0, v0
	v_mov_b32_e32 v8, v160
	s_cmpk_lt_i32 s12, 0x380
	s_cselect_b64 s[2:3], -1, 0
	s_waitcnt lgkmcnt(0)
	v_readfirstlane_b32 s0, v0
	s_cmpk_gt_i32 s12, 0x37f
	s_nop 0
	v_writelane_b32 v255, s0, 6
	v_readfirstlane_b32 s0, v8
	s_cbranch_scc1 .LBB0_228
	s_ashr_i32 s1, s12, 31
	s_lshr_b32 s1, s1, 29
	s_add_i32 s1, s12, s1
	s_ashr_i32 s4, s1, 3
	s_and_b32 s1, s1, -8
	s_sub_i32 s1, s12, s1
	s_cmp_lt_i32 s1, 0
	s_movk_i32 s5, 0x71
	s_cselect_b32 s5, s5, 0x70
	s_mul_i32 s1, s1, s5
	s_add_i32 s1, s1, s4
	s_mul_hi_i32 s4, s1, 0x92492493
	s_add_i32 s4, s4, s1
	s_lshr_b32 s5, s4, 31
	s_ashr_i32 s4, s4, 5
	s_add_i32 s4, s4, s5
	s_lshl_b32 s5, s4, 2
	s_mul_i32 s4, s4, 56
	s_sub_i32 s1, s1, s4
	s_bfe_i32 s4, s1, 0x80000
	s_bfe_u32 s4, s4, 0x2000d
	s_add_i32 s4, s1, s4
	s_bfe_i32 s6, s4, 0x80000
	s_and_b32 s4, s4, 0xfc
	s_sub_i32 s1, s1, s4
	s_sext_i32_i16 s7, s6
	s_sext_i32_i8 s1, s1
	s_add_i32 s6, s5, s1
	s_ashr_i32 s66, s7, 2

; #define PG8_WAIT_V(n) asm volatile("s_waitcnt vmcnt(" #n ")" ::: "memory")
; #define PG8_BAR __builtin_amdgcn_s_barrier()
; template <class Epi, class Sched, bool ALIGN_EPI = false, bool SP2 = false>
; __device__ __forceinline__ void gemm_phase(PG8_LAS unsigned char* lds, const Gemm g, const Sched& S, const Epi& E) {
;     ...
;     PG8_WAIT_V(0);
;     if constexpr (!ALIGN_EPI) { if (wr == 0) PG8_BAR; }
;     PG8_BAR;
.LBB0_463:
	s_nop 0
	s_waitcnt vmcnt(0)
	v_readlane_b32 s88, v255, 1
	v_readlane_b32 s89, v255, 2
	s_barrier
